# layer 0 also runs 40 w_out tiles in the dual-projection tail; layer-1 weight conversion split over the in-proj tail (192 idle workgroups), the projection tail and the w_out tail
# speedup vs baseline: 1.0072x; 1.0042x over previous
; __device__ __forceinline__ int launder(int v) { asm volatile("" : "+v"(v)); return v; }
; __device__ __forceinline__ void run_phase(const Params& p, int ph, LAS unsigned char* lds, const int tid, const int bid) {
;     ...
;         if (l == 0 && bid >= 40) for (int it = 1440 + bid - 40; it < 2880; it += G - 40) conv_item(p, 1, it, lds, launder(tid)); }
.LBB0_96:
	s_cmpk_lg_u32 s42, 0x100
	s_cbranch_scc1 .Ly3_old96
	s_andn2_b64 vcc, exec, s[0:1]
	s_cbranch_vccnz .LBB0_139
	s_cmp_eq_u32 s81, 6
	s_cbranch_scc0 .LBB0_139
	s_add_i32 s18, s82, 0x930
	s_movk_i32 s19, 0x100
	s_movk_i32 s20, 0xb40
	s_mov_b32 s21, 1
	s_mov_b32 s22, 2
	s_branch .Lcva_run

; __device__ __forceinline__ int launder(int v) { asm volatile("" : "+v"(v)); return v; }
; __device__ __forceinline__ void run_phase(const Params& p, int ph, LAS unsigned char* lds, const int tid, const int bid) {
;     ...
;         if (l == 0 && bid >= 80) for (int it = bid - 80; it < 1440; it += G - 80) conv_item(p, 1, it, lds, launder(tid)); }
.Lp5_noshadow:
	s_cmp_lt_u32 s81, 7
	s_cselect_b64 s[0:1], -1, 0
	s_cmpk_gt_i32 s82, 0x4f
	s_cselect_b64 s[6:7], -1, 0
	s_cmpk_lt_u32 s82, 0x5f0
	s_cselect_b64 s[8:9], -1, 0
	s_and_b64 s[0:1], s[0:1], s[8:9]
	s_and_b64 s[0:1], s[0:1], s[6:7]
	s_andn2_b64 vcc, exec, s[0:1]
	s_cbranch_vccnz .LBB0_281
	s_add_i32 s18, s82, 0xffffffb0
	s_add_i32 s19, s42, 0xffffffb0
	s_movk_i32 s20, 0x5a0
	s_cmpk_lg_u32 s42, 0x100
	s_cbranch_scc1 .Ly3_p5old
	s_add_i32 s18, s82, 0x588
	s_movk_i32 s19, 0x88
	s_movk_i32 s20, 0x930

; __device__ __forceinline__ void run_phase(const Params& p, int ph, LAS unsigned char* lds, const int tid, const int bid) {
;     ...
;         SchedPlain S; S.init(MPAD, NIN, G, bid); S.A = pws(p) + OFF_XB; S.Bt = pws(p) + OFF_WIN + l * SZ_WIN; S.tstepA = (size_t)256 * D * 2; S.tstepB = (size_t)256 * D * 2;
;         EpiWin E; E.u = (float*)(pws(p) + OFF_U); E.zb = (bf16_t*)(pws(p) + OFF_ZB); E.rsq = (const float*)(pws(p) + OFF_RSQ) + (size_t)l * MPAD; E.cf = (const float*)(pws(p) + OFF_CS);
;         gemm_phase(lds, S, E, D, D, D, tid); }
.LBB0_581:
	s_barrier
	s_cmp_eq_u32 s81, 1
	s_cbranch_scc0 .LBB0_582
	s_cmpk_lg_u32 s42, 0x100
	s_cbranch_scc1 .LBB0_582
	s_cmpk_lt_u32 s82, 64
	s_cbranch_scc1 .LBB0_582
	s_add_i32 s18, s82, 0xffffffc0
	s_movk_i32 s19, 0xc0
	s_movk_i32 s20, 0x600
	s_mov_b32 s21, 1
	s_mov_b32 s22, 3
	s_branch .Lcvb_run
